# v23 + strategy 7.4: one static s_setprio 1 for the trailing wave group (waves 4-7) through the NSA phase, reset at the next phase entry
# speedup vs baseline: 1.0047x; 1.0047x over previous
.LBB0_1471:
	s_load_dwordx2 s[2:3], s[0:1], 0x310
	s_waitcnt lgkmcnt(0)
	s_cmp_lt_i32 s2, 16
	s_cselect_b64 s[2:3], -1, 0
	s_and_b64 s[4:5], s[2:3], s[6:7]
	s_andn2_b64 vcc, exec, s[4:5]
	s_cbranch_vccnz .LBB0_2070
	s_load_dwordx4 s[8:11], s[0:1], 0xd0
	v_readfirstlane_b32 s2, v0
	v_writelane_b32 v250, s4, 8
	s_lshr_b32 s3, s2, 6
	s_cmp_lt_u32 s3, 4
	s_cbranch_scc1 .Lprio_skip
	s_setprio 1
.Lprio_skip:
	v_lshlrev_b32_e32 v3, 3, v0
	v_writelane_b32 v250, s5, 9
	s_waitcnt lgkmcnt(0)
	s_add_u32 s4, s10, 0x23510000
	v_writelane_b32 v250, s85, 10
	s_addc_u32 s5, s11, 0
	v_writelane_b32 v250, s4, 11
	s_add_u32 s2, s10, 0x7910000
	v_lshlrev_b32_e32 v10, 4, v0
	v_writelane_b32 v250, s5, 12
	v_writelane_b32 v250, s2, 13
	s_addc_u32 s2, s11, 0
	v_writelane_b32 v250, s2, 14
	s_add_u32 s2, s10, 0x7b10000
	v_writelane_b32 v250, s2, 15
	s_addc_u32 s2, s11, 0
	s_cmpk_lg_i32 s80, 0x100
	v_writelane_b32 v250, s2, 16
	s_cselect_b64 s[4:5], -1, 0
	v_writelane_b32 v250, s4, 17
	s_ashr_i32 s2, s76, 3
	s_lshl_b32 s81, s3, 2
	v_writelane_b32 v250, s5, 18
	v_writelane_b32 v250, s2, 19
	s_lshl_b32 s2, s76, 1
	s_and_b32 s2, s2, 14
	v_writelane_b32 v250, s2, 20
	s_sub_i32 s2, s81, 31
	v_lshlrev_b32_e32 v12, 1, v0
	v_and_b32_e32 v2, 0x78, v3
	v_bfe_u32 v7, v3, 5, 2
	v_and_b32_e32 v11, 0xc0, v10
	v_and_b32_e32 v12, 32, v12
	v_and_b32_e32 v3, 0x118, v3
	s_cmp_lg_u32 0, -1
	v_writelane_b32 v250, s2, 21
	v_or3_b32 v3, v12, v11, v3
	s_cselect_b32 s2, 0, 0
	v_add_u32_e32 v180, s2, v3
	s_lshl_b32 s2, s3, 8
	s_add_i32 s2, s2, 0
	s_add_i32 s33, s2, 0x14000
	s_lshl_b32 s2, s3, 13
	s_add_i32 s2, s2, 0
	s_add_i32 s83, s2, 0x14800
	s_lshl_b32 s2, s3, 12
	s_add_i32 s89, s2, 0
	s_add_i32 s2, 0, 0x10000
	v_writelane_b32 v250, s3, 22
	s_lshl_b32 s3, s3, 5
	s_add_i32 s3, s2, s3
	v_writelane_b32 v250, s3, 23
	s_or_b32 s3, s81, 1
	s_lshl_b32 s4, s3, 10
	s_add_i32 s4, s4, 0
	s_lshl_b32 s3, s3, 3
	v_writelane_b32 v250, s4, 24
	s_add_i32 s3, s2, s3
	v_writelane_b32 v250, s3, 25
	s_or_b32 s3, s81, 2
	s_lshl_b32 s4, s3, 10
	v_lshrrev_b32_e32 v178, 4, v0
	v_lshrrev_b32_e32 v4, 3, v0
	s_add_i32 s4, s4, 0
	s_lshl_b32 s3, s3, 3
	v_and_b32_e32 v4, 8, v4
	v_or_b32_e32 v179, 32, v178
	v_writelane_b32 v250, s4, 26
	s_add_i32 s3, s2, s3
	v_and_or_b32 v5, v178, 16, v4
	v_and_or_b32 v4, v179, 48, v4
	v_writelane_b32 v250, s3, 27
	s_or_b32 s3, s81, 3
	v_lshrrev_b32_e32 v6, 5, v0
	v_lshrrev_b32_e32 v5, 1, v5
	v_bfe_u32 v8, v0, 4, 2
	v_lshrrev_b32_e32 v4, 1, v4
	s_lshl_b32 s4, s3, 10
	v_or_b32_e32 v5, v5, v7
	v_and_or_b32 v6, v6, 4, v8
	v_lshlrev_b32_e32 v8, 1, v2
	v_or_b32_e32 v4, v4, v7
	s_add_i32 s4, s4, 0
	s_lshl_b32 s3, s3, 3
	v_lshlrev_b32_e32 v5, 9, v5
	v_lshlrev_b32_e32 v6, 6, v6
	v_and_b32_e32 v9, 48, v8
	v_lshlrev_b32_e32 v4, 9, v4
	v_bfe_u32 v11, v0, 5, 1
	v_writelane_b32 v250, s4, 28
	s_add_i32 s2, s2, s3
	v_or3_b32 v7, v4, v6, v9
	v_and_b32_e32 v4, 0x70, v0
	v_or3_b32 v5, v5, v6, v9
	v_lshlrev_b32_e32 v6, 8, v178
	v_lshlrev_b32_e32 v182, 4, v11
	v_writelane_b32 v250, s2, 29
	s_add_u32 s2, s10, 0x23513800
	v_bitop3_b32 v9, v8, v6, v4 bitop3:0xde
	v_and_b32_e32 v8, 0x70, v10
	v_or_b32_e32 v10, 32, v182
	s_addc_u32 s3, s11, 0
	v_xad_u32 v184, v10, v8, 0
	v_or_b32_e32 v10, 64, v182
	v_writelane_b32 v250, s2, 30
	v_xad_u32 v185, v10, v8, 0
	v_or_b32_e32 v10, 0x60, v182
	v_writelane_b32 v250, s3, 31
	v_and_b32_e32 v176, 63, v0
	v_and_b32_e32 v177, 31, v0
	v_lshlrev_b32_e32 v4, 10, v178
	v_lshlrev_b32_e32 v6, 10, v179
	v_xad_u32 v183, v182, v8, 0
	v_xad_u32 v186, v10, v8, 0
	v_mul_u32_u24_e32 v8, 0x1d00, v178
	v_writelane_b32 v250, s86, 32
	s_mov_b32 s85, 0
	v_mov_b32_e32 v3, 0
	v_lshlrev_b32_e32 v181, 8, v177
	v_mul_i32_i24_e32 v187, -4, v11
	v_cmp_gt_u32_e64 s[6:7], 32, v176
	s_movk_i32 s3, 0x3a00
	s_waitcnt vmcnt(0)
	v_lshlrev_b32_e32 v154, 1, v4
	v_lshlrev_b32_e32 v156, 1, v6
	v_add_u32_e32 v188, 0, v9
	v_add_u32_e32 v189, 0, v5
	v_add_u32_e32 v190, 0, v7
	s_mov_b32 s76, 0x41000000
	s_movk_i32 s77, 0x200
	v_lshlrev_b32_e32 v158, 1, v8
	s_brev_b32 s82, -2
	v_lshlrev_b32_e32 v160, 1, v2
	v_mov_b32_e32 v191, 0xff800000
	v_mov_b32_e32 v192, 0x4e6e6b28
	v_mov_b32_e32 v193, 0xf149f2ca
	s_mov_b32 s96, 0
	v_writelane_b32 v250, s87, 33
	v_writelane_b32 v250, s89, 34
	s_branch .LBB0_1475

.LBB0_2124:
	s_setprio 0
	s_load_dwordx2 s[4:5], s[0:1], 0x310
	s_waitcnt lgkmcnt(0)
	s_cmp_lt_i32 s4, 19
	s_cselect_b64 s[2:3], -1, 0
	s_cmp_gt_i32 s5, 18
	s_cselect_b64 s[4:5], -1, 0
	s_and_b64 s[4:5], s[2:3], s[4:5]
	s_andn2_b64 vcc, exec, s[4:5]
	s_cbranch_vccnz .LBB0_2149
	s_cmpk_gt_i32 s76, 0x3ff
	v_readfirstlane_b32 s16, v0
	s_cbranch_scc1 .LBB0_2149
	s_ashr_i32 s3, s76, 31
	s_lshr_b32 s2, s3, 29
	s_add_i32 s2, s76, s2
	s_and_b32 s6, s2, -8
	s_sub_i32 s9, s76, s6
	s_cmp_gt_i32 s9, -1
	s_cbranch_scc0 .LBB0_2128
	s_lshl_b32 s8, s9, 7
	s_cbranch_execz .LBB0_2129
	s_branch .LBB0_2130
